# grid barrier: leader also invalidates early and releases locals without waiting for it (on v24)
# speedup vs baseline: 1.0097x; 1.0017x over previous
.LBB0_151:
	s_or_b64 exec, exec, s[14:15]
	v_cvt_f32_u32_e32 v3, v0
	s_waitcnt vmcnt(0)
	v_readfirstlane_b32 s3, v2
	buffer_inv sc1
	s_add_u32 s14, s8, 0xe003500
	s_addc_u32 s15, s9, 0
	v_rcp_iflag_f32_e32 v3, v3
	v_add_u32_e32 v1, s3, v1
	v_add_u32_e32 v4, 1, v1
	s_mov_b64 s[16:17], -1
	v_mul_f32_e32 v2, 0x4f7ffffe, v3
	v_cvt_u32_f32_e32 v2, v2
	v_sub_u32_e32 v3, 0, v0
	v_mul_lo_u32 v3, v3, v2
	v_mul_hi_u32 v3, v2, v3
	v_add_u32_e32 v2, v2, v3
	v_mul_hi_u32 v2, v1, v2
	v_mul_lo_u32 v3, v2, v0
	v_sub_u32_e32 v1, v1, v3
	v_add_u32_e32 v5, 1, v2
	v_cmp_ge_u32_e32 vcc, v1, v0
	v_sub_u32_e32 v3, v1, v0
	s_nop 0
	v_cndmask_b32_e32 v2, v2, v5, vcc
	v_cndmask_b32_e32 v1, v1, v3, vcc
	v_add_u32_e32 v3, 1, v2
	v_cmp_ge_u32_e32 vcc, v1, v0
	s_nop 1
	v_cndmask_b32_e32 v2, v2, v3, vcc
	v_mul_lo_u32 v1, v0, v2
	v_add_u32_e32 v0, v1, v0
	v_cmp_ne_u32_e32 vcc, v4, v0
	v_mov_b64_e32 v[0:1], s[14:15]
	s_and_saveexec_b64 s[12:13], vcc
	s_cbranch_execz .LBB0_163
	v_mov_b32_e32 v0, 0
	global_load_dword v1, v0, s[14:15] sc1
	s_mov_b64 s[20:21], 0
	s_waitcnt vmcnt(0)
	v_cmp_eq_u32_e32 vcc, v1, v2
	s_and_saveexec_b64 s[18:19], vcc
	s_cbranch_execz .LBB0_162
	s_add_u32 s16, s8, 0xe000200
	s_addc_u32 s17, s9, 0
	s_mov_b32 s3, 1
	s_mov_b64 s[8:9], 0
	s_branch .LBB0_155

.LBB0_165:
	s_or_b64 exec, exec, s[8:9]
	s_mov_b64 s[8:9], exec
	v_mbcnt_lo_u32_b32 v0, s8, 0
	v_mbcnt_hi_u32_b32 v0, s9, v0
	v_cmp_eq_u32_e32 vcc, 0, v0
	s_and_saveexec_b64 s[12:13], vcc
	s_cbranch_execz .LBB0_167
	s_bcnt1_i32_b64 s3, s[8:9]
	v_mov_b32_e32 v0, 0x2000
	v_mov_b32_e32 v1, s3
	global_atomic_add v0, v1, s[10:11] offset:1024

.LBB0_454:
	s_or_b64 exec, exec, s[16:17]
	v_cvt_f32_u32_e32 v3, v0
	s_waitcnt vmcnt(0)
	v_readfirstlane_b32 s14, v2
	buffer_inv sc1
	s_add_u32 s16, s10, 0xe003500
	s_addc_u32 s17, s11, 0
	v_rcp_iflag_f32_e32 v3, v3
	v_add_u32_e32 v1, s14, v1
	v_add_u32_e32 v4, 1, v1
	s_mov_b64 s[18:19], -1
	v_mul_f32_e32 v2, 0x4f7ffffe, v3
	v_cvt_u32_f32_e32 v2, v2
	v_sub_u32_e32 v3, 0, v0
	v_mul_lo_u32 v3, v3, v2
	v_mul_hi_u32 v3, v2, v3
	v_add_u32_e32 v2, v2, v3
	v_mul_hi_u32 v2, v1, v2
	v_mul_lo_u32 v3, v2, v0
	v_sub_u32_e32 v1, v1, v3
	v_add_u32_e32 v5, 1, v2
	v_cmp_ge_u32_e32 vcc, v1, v0
	v_sub_u32_e32 v3, v1, v0
	s_nop 0
	v_cndmask_b32_e32 v2, v2, v5, vcc
	v_cndmask_b32_e32 v1, v1, v3, vcc
	v_add_u32_e32 v3, 1, v2
	v_cmp_ge_u32_e32 vcc, v1, v0
	s_nop 1
	v_cndmask_b32_e32 v2, v2, v3, vcc
	v_mul_lo_u32 v1, v0, v2
	v_add_u32_e32 v0, v1, v0
	v_cmp_ne_u32_e32 vcc, v4, v0
	v_mov_b64_e32 v[0:1], s[16:17]
	s_and_saveexec_b64 s[14:15], vcc
	s_cbranch_execz .LBB0_466
	v_mov_b32_e32 v0, 0
	global_load_dword v1, v0, s[16:17] sc1
	s_mov_b64 s[34:35], 0
	s_waitcnt vmcnt(0)
	v_cmp_eq_u32_e32 vcc, v1, v2
	s_and_saveexec_b64 s[22:23], vcc
	s_cbranch_execz .LBB0_465
	s_add_u32 s18, s10, 0xe000200
	s_addc_u32 s19, s11, 0
	s_mov_b32 s26, 1
	s_mov_b64 s[10:11], 0
	s_branch .LBB0_458

.LBB0_468:
	s_or_b64 exec, exec, s[10:11]
	s_mov_b64 s[10:11], exec
	v_mbcnt_lo_u32_b32 v0, s10, 0
	v_mbcnt_hi_u32_b32 v0, s11, v0
	v_cmp_eq_u32_e32 vcc, 0, v0
	s_and_saveexec_b64 s[14:15], vcc
	s_cbranch_execz .LBB0_470
	s_bcnt1_i32_b64 s10, s[10:11]
	v_mov_b32_e32 v0, 0x2000
	v_mov_b32_e32 v1, s10
	global_atomic_add v0, v1, s[12:13] offset:1024

.LBB0_609:
	s_or_b64 exec, exec, s[16:17]
	v_cvt_f32_u32_e32 v3, v0
	s_waitcnt vmcnt(0)
	v_readfirstlane_b32 s14, v2
	buffer_inv sc1
	s_add_u32 s16, s10, 0xe003500
	s_addc_u32 s17, s11, 0
	v_rcp_iflag_f32_e32 v3, v3
	v_add_u32_e32 v1, s14, v1
	v_add_u32_e32 v4, 1, v1
	s_mov_b64 s[18:19], -1
	v_mul_f32_e32 v2, 0x4f7ffffe, v3
	v_cvt_u32_f32_e32 v2, v2
	v_sub_u32_e32 v3, 0, v0
	v_mul_lo_u32 v3, v3, v2
	v_mul_hi_u32 v3, v2, v3
	v_add_u32_e32 v2, v2, v3
	v_mul_hi_u32 v2, v1, v2
	v_mul_lo_u32 v3, v2, v0
	v_sub_u32_e32 v1, v1, v3
	v_add_u32_e32 v5, 1, v2
	v_cmp_ge_u32_e32 vcc, v1, v0
	v_sub_u32_e32 v3, v1, v0
	s_nop 0
	v_cndmask_b32_e32 v2, v2, v5, vcc
	v_cndmask_b32_e32 v1, v1, v3, vcc
	v_add_u32_e32 v3, 1, v2
	v_cmp_ge_u32_e32 vcc, v1, v0
	s_nop 1
	v_cndmask_b32_e32 v2, v2, v3, vcc
	v_mul_lo_u32 v1, v0, v2
	v_add_u32_e32 v0, v1, v0
	v_cmp_ne_u32_e32 vcc, v4, v0
	v_mov_b64_e32 v[0:1], s[16:17]
	s_and_saveexec_b64 s[14:15], vcc
	s_cbranch_execz .LBB0_621
	v_mov_b32_e32 v0, 0
	global_load_dword v1, v0, s[16:17] sc1
	s_mov_b64 s[36:37], 0
	s_waitcnt vmcnt(0)
	v_cmp_eq_u32_e32 vcc, v1, v2
	s_and_saveexec_b64 s[34:35], vcc
	s_cbranch_execz .LBB0_620
	s_add_u32 s18, s10, 0xe000200
	s_addc_u32 s19, s11, 0
	s_mov_b32 s26, 1
	s_mov_b64 s[10:11], 0
	s_branch .LBB0_613

.LBB0_1023:
	s_or_b64 exec, exec, s[18:19]
	v_cvt_f32_u32_e32 v3, v0
	s_waitcnt vmcnt(0)
	v_readfirstlane_b32 s16, v2
	buffer_inv sc1
	s_add_u32 s18, s12, 0xe003500
	s_addc_u32 s19, s13, 0
	v_rcp_iflag_f32_e32 v3, v3
	v_add_u32_e32 v1, s16, v1
	v_add_u32_e32 v4, 1, v1
	s_mov_b64 s[36:37], -1
	v_mul_f32_e32 v2, 0x4f7ffffe, v3
	v_cvt_u32_f32_e32 v2, v2
	v_sub_u32_e32 v3, 0, v0
	v_mul_lo_u32 v3, v3, v2
	v_mul_hi_u32 v3, v2, v3
	v_add_u32_e32 v2, v2, v3
	v_mul_hi_u32 v2, v1, v2
	v_mul_lo_u32 v3, v2, v0
	v_sub_u32_e32 v1, v1, v3
	v_add_u32_e32 v5, 1, v2
	v_cmp_ge_u32_e32 vcc, v1, v0
	v_sub_u32_e32 v3, v1, v0
	s_nop 0
	v_cndmask_b32_e32 v2, v2, v5, vcc
	v_cndmask_b32_e32 v1, v1, v3, vcc
	v_add_u32_e32 v3, 1, v2
	v_cmp_ge_u32_e32 vcc, v1, v0
	s_nop 1
	v_cndmask_b32_e32 v2, v2, v3, vcc
	v_mul_lo_u32 v1, v0, v2
	v_add_u32_e32 v0, v1, v0
	v_cmp_ne_u32_e32 vcc, v4, v0
	v_mov_b64_e32 v[0:1], s[18:19]
	s_and_saveexec_b64 s[16:17], vcc
	s_cbranch_execz .LBB0_1035
	v_mov_b32_e32 v0, 0
	global_load_dword v1, v0, s[18:19] sc1
	s_mov_b64 s[40:41], 0
	s_waitcnt vmcnt(0)
	v_cmp_eq_u32_e32 vcc, v1, v2
	s_and_saveexec_b64 s[38:39], vcc
	s_cbranch_execz .LBB0_1034
	s_add_u32 s36, s12, 0xe000200
	s_addc_u32 s37, s13, 0
	s_mov_b32 s26, 1
	s_mov_b64 s[12:13], 0
	s_branch .LBB0_1027

.LBB0_1037:
	s_or_b64 exec, exec, s[12:13]
	s_mov_b64 s[12:13], exec
	v_mbcnt_lo_u32_b32 v0, s12, 0
	v_mbcnt_hi_u32_b32 v0, s13, v0
	v_cmp_eq_u32_e32 vcc, 0, v0
	s_and_saveexec_b64 s[16:17], vcc
	s_cbranch_execz .LBB0_1039
	s_bcnt1_i32_b64 s12, s[12:13]
	v_mov_b32_e32 v0, 0x2000
	v_mov_b32_e32 v1, s12
	global_atomic_add v0, v1, s[14:15] offset:1024

.LBB0_1324:
	s_or_b64 exec, exec, s[18:19]
	v_cvt_f32_u32_e32 v3, v0
	s_waitcnt vmcnt(0)
	v_readfirstlane_b32 s16, v2
	buffer_inv sc1
	s_add_u32 s18, s12, 0xe003500
	s_addc_u32 s19, s13, 0
	v_rcp_iflag_f32_e32 v3, v3
	v_add_u32_e32 v1, s16, v1
	v_add_u32_e32 v4, 1, v1
	s_mov_b64 s[20:21], -1
	v_mul_f32_e32 v2, 0x4f7ffffe, v3
	v_cvt_u32_f32_e32 v2, v2
	v_sub_u32_e32 v3, 0, v0
	v_mul_lo_u32 v3, v3, v2
	v_mul_hi_u32 v3, v2, v3
	v_add_u32_e32 v2, v2, v3
	v_mul_hi_u32 v2, v1, v2
	v_mul_lo_u32 v3, v2, v0
	v_sub_u32_e32 v1, v1, v3
	v_add_u32_e32 v5, 1, v2
	v_cmp_ge_u32_e32 vcc, v1, v0
	v_sub_u32_e32 v3, v1, v0
	s_nop 0
	v_cndmask_b32_e32 v2, v2, v5, vcc
	v_cndmask_b32_e32 v1, v1, v3, vcc
	v_add_u32_e32 v3, 1, v2
	v_cmp_ge_u32_e32 vcc, v1, v0
	s_nop 1
	v_cndmask_b32_e32 v2, v2, v3, vcc
	v_mul_lo_u32 v1, v0, v2
	v_add_u32_e32 v0, v1, v0
	v_cmp_ne_u32_e32 vcc, v4, v0
	v_mov_b64_e32 v[0:1], s[18:19]
	s_and_saveexec_b64 s[16:17], vcc
	s_cbranch_execz .LBB0_1336
	v_mov_b32_e32 v0, 0
	global_load_dword v1, v0, s[18:19] sc1
	s_mov_b64 s[38:39], 0
	s_waitcnt vmcnt(0)
	v_cmp_eq_u32_e32 vcc, v1, v2
	s_and_saveexec_b64 s[36:37], vcc
	s_cbranch_execz .LBB0_1335
	s_add_u32 s20, s12, 0xe000200
	s_addc_u32 s21, s13, 0
	s_mov_b32 s26, 1
	s_mov_b64 s[12:13], 0
	s_branch .LBB0_1328

.LBB0_1479:
	s_or_b64 exec, exec, s[18:19]
	v_cvt_f32_u32_e32 v3, v0
	s_waitcnt vmcnt(0)
	v_readfirstlane_b32 s16, v2
	buffer_inv sc1
	s_add_u32 s18, s12, 0xe003500
	s_addc_u32 s19, s13, 0
	v_rcp_iflag_f32_e32 v3, v3
	v_add_u32_e32 v1, s16, v1
	v_add_u32_e32 v4, 1, v1
	s_mov_b64 s[20:21], -1
	v_mul_f32_e32 v2, 0x4f7ffffe, v3
	v_cvt_u32_f32_e32 v2, v2
	v_sub_u32_e32 v3, 0, v0
	v_mul_lo_u32 v3, v3, v2
	v_mul_hi_u32 v3, v2, v3
	v_add_u32_e32 v2, v2, v3
	v_mul_hi_u32 v2, v1, v2
	v_mul_lo_u32 v3, v2, v0
	v_sub_u32_e32 v1, v1, v3
	v_add_u32_e32 v5, 1, v2
	v_cmp_ge_u32_e32 vcc, v1, v0
	v_sub_u32_e32 v3, v1, v0
	s_nop 0
	v_cndmask_b32_e32 v2, v2, v5, vcc
	v_cndmask_b32_e32 v1, v1, v3, vcc
	v_add_u32_e32 v3, 1, v2
	v_cmp_ge_u32_e32 vcc, v1, v0
	s_nop 1
	v_cndmask_b32_e32 v2, v2, v3, vcc
	v_mul_lo_u32 v1, v0, v2
	v_add_u32_e32 v0, v1, v0
	v_cmp_ne_u32_e32 vcc, v4, v0
	v_mov_b64_e32 v[0:1], s[18:19]
	s_and_saveexec_b64 s[16:17], vcc
	s_cbranch_execz .LBB0_1491
	v_mov_b32_e32 v0, 0
	global_load_dword v1, v0, s[18:19] sc1
	s_mov_b64 s[36:37], 0
	s_waitcnt vmcnt(0)
	v_cmp_eq_u32_e32 vcc, v1, v2
	s_and_saveexec_b64 s[22:23], vcc
	s_cbranch_execz .LBB0_1490
	s_add_u32 s20, s12, 0xe000200
	s_addc_u32 s21, s13, 0
	s_mov_b32 s26, 1
	s_mov_b64 s[12:13], 0
	s_branch .LBB0_1483

.LBB0_1797:
	s_or_b64 exec, exec, s[18:19]
	v_cvt_f32_u32_e32 v3, v0
	s_waitcnt vmcnt(0)
	v_readfirstlane_b32 s16, v2
	buffer_inv sc1
	s_add_u32 s18, s10, 0xe003500
	s_addc_u32 s19, s11, 0
	v_rcp_iflag_f32_e32 v3, v3
	v_add_u32_e32 v1, s16, v1
	v_add_u32_e32 v4, 1, v1
	s_mov_b64 s[20:21], -1
	v_mul_f32_e32 v2, 0x4f7ffffe, v3
	v_cvt_u32_f32_e32 v2, v2
	v_sub_u32_e32 v3, 0, v0
	v_mul_lo_u32 v3, v3, v2
	v_mul_hi_u32 v3, v2, v3
	v_add_u32_e32 v2, v2, v3
	v_mul_hi_u32 v2, v1, v2
	v_mul_lo_u32 v3, v2, v0
	v_sub_u32_e32 v1, v1, v3
	v_add_u32_e32 v5, 1, v2
	v_cmp_ge_u32_e32 vcc, v1, v0
	v_sub_u32_e32 v3, v1, v0
	s_nop 0
	v_cndmask_b32_e32 v2, v2, v5, vcc
	v_cndmask_b32_e32 v1, v1, v3, vcc
	v_add_u32_e32 v3, 1, v2
	v_cmp_ge_u32_e32 vcc, v1, v0
	s_nop 1
	v_cndmask_b32_e32 v2, v2, v3, vcc
	v_mul_lo_u32 v1, v0, v2
	v_add_u32_e32 v0, v1, v0
	v_cmp_ne_u32_e32 vcc, v4, v0
	v_mov_b64_e32 v[0:1], s[18:19]
	s_and_saveexec_b64 s[16:17], vcc
	s_cbranch_execz .LBB0_1809
	v_mov_b32_e32 v0, 0
	global_load_dword v1, v0, s[18:19] sc1
	s_mov_b64 s[34:35], 0
	s_waitcnt vmcnt(0)
	v_cmp_eq_u32_e32 vcc, v1, v2
	s_and_saveexec_b64 s[22:23], vcc
	s_cbranch_execz .LBB0_1808
	s_add_u32 s20, s10, 0xe000200
	s_addc_u32 s21, s11, 0
	s_mov_b32 s26, 1
	s_mov_b64 s[10:11], 0
	s_branch .LBB0_1801

.LBB0_1811:
	s_or_b64 exec, exec, s[10:11]
	s_mov_b64 s[10:11], exec
	v_mbcnt_lo_u32_b32 v0, s10, 0
	v_mbcnt_hi_u32_b32 v0, s11, v0
	v_cmp_eq_u32_e32 vcc, 0, v0
	s_and_saveexec_b64 s[16:17], vcc
	s_cbranch_execz .LBB0_1813
	s_bcnt1_i32_b64 s10, s[10:11]
	v_mov_b32_e32 v0, 0x2000
	v_mov_b32_e32 v1, s10
	global_atomic_add v0, v1, s[12:13] offset:1024

.LBB0_1893:
	s_or_b64 exec, exec, s[20:21]
	v_cvt_f32_u32_e32 v3, v0
	s_waitcnt vmcnt(0)
	v_readfirstlane_b32 s18, v2
	buffer_inv sc1
	s_add_u32 s20, s4, 0xe003500
	s_addc_u32 s21, s5, 0
	v_rcp_iflag_f32_e32 v3, v3
	v_add_u32_e32 v1, s18, v1
	v_add_u32_e32 v4, 1, v1
	s_mov_b64 s[22:23], -1
	v_mul_f32_e32 v2, 0x4f7ffffe, v3
	v_cvt_u32_f32_e32 v2, v2
	v_sub_u32_e32 v3, 0, v0
	v_mul_lo_u32 v3, v3, v2
	v_mul_hi_u32 v3, v2, v3
	v_add_u32_e32 v2, v2, v3
	v_mul_hi_u32 v2, v1, v2
	v_mul_lo_u32 v3, v2, v0
	v_sub_u32_e32 v1, v1, v3
	v_add_u32_e32 v5, 1, v2
	v_cmp_ge_u32_e32 vcc, v1, v0
	v_sub_u32_e32 v3, v1, v0
	s_nop 0
	v_cndmask_b32_e32 v2, v2, v5, vcc
	v_cndmask_b32_e32 v1, v1, v3, vcc
	v_add_u32_e32 v3, 1, v2
	v_cmp_ge_u32_e32 vcc, v1, v0
	s_nop 1
	v_cndmask_b32_e32 v2, v2, v3, vcc
	v_mul_lo_u32 v1, v0, v2
	v_add_u32_e32 v0, v1, v0
	v_cmp_ne_u32_e32 vcc, v4, v0
	v_mov_b64_e32 v[0:1], s[20:21]
	s_and_saveexec_b64 s[18:19], vcc
	s_cbranch_execz .LBB0_1905
	v_mov_b32_e32 v0, 0
	global_load_dword v1, v0, s[20:21] sc1
	s_mov_b64 s[36:37], 0
	s_waitcnt vmcnt(0)
	v_cmp_eq_u32_e32 vcc, v1, v2
	s_and_saveexec_b64 s[34:35], vcc
	s_cbranch_execz .LBB0_1904
	s_add_u32 s22, s4, 0xe000200
	s_addc_u32 s23, s5, 0
	s_mov_b32 s25, 1
	s_mov_b64 s[4:5], 0
	s_branch .LBB0_1897

.LBB0_1907:
	s_or_b64 exec, exec, s[4:5]
	s_mov_b64 s[4:5], exec
	v_mbcnt_lo_u32_b32 v0, s4, 0
	v_mbcnt_hi_u32_b32 v0, s5, v0
	v_cmp_eq_u32_e32 vcc, 0, v0
	s_and_saveexec_b64 s[18:19], vcc
	s_cbranch_execz .LBB0_1909
	s_bcnt1_i32_b64 s4, s[4:5]
	v_mov_b32_e32 v0, 0x2000
	v_mov_b32_e32 v1, s4
	global_atomic_add v0, v1, s[10:11] offset:1024
